# attention wave priorities: serial sections (checks, DMA issue, pair barrier) prio 2, P.V block prio 1, QK block prio 0
# baseline (speedup 1.0000x reference)
.LBB0_940:
	s_setprio 0
	s_add_i32 s6, s80, 0xffffe000
	s_and_b32 s6, s6, 0x6000
	s_add_i32 s6, s6, 0
	s_add_i32 s6, s6, 0x14000
	v_add_u32_e32 v3, s6, v206
	v_add_u32_e32 v8, s6, v210
	ds_read_b128 v[4:7], v3
	ds_read_b128 v[8:11], v8 offset:4096
	s_waitcnt lgkmcnt(1)
	v_mfma_f32_32x32x16_bf16 v[132:147], v[4:7], v[176:179], v[82:97]
	v_add_u32_e32 v3, s6, v207
	ds_read_b128 v[12:15], v3
	v_add_u32_e32 v3, s6, v211
	ds_read_b128 v[216:219], v3 offset:4096
	v_add_f32_e32 v3, 0, v100
	v_add_f32_e32 v3, v101, v3
	v_add_f32_e32 v3, v102, v3
	v_add_f32_e32 v3, v103, v3
	v_cvt_pk_bf16_f32 v180, v100, v101
	v_cvt_pk_bf16_f32 v181, v102, v103
	s_waitcnt lgkmcnt(2)
	v_mfma_f32_32x32x16_bf16 v[148:163], v[8:11], v[176:179], v[82:97]
	v_add_f32_e32 v3, v104, v3
	v_add_f32_e32 v3, v105, v3
	v_add_f32_e32 v3, v106, v3
	v_add_f32_e32 v3, v107, v3
	v_cvt_pk_bf16_f32 v182, v104, v105
	v_cvt_pk_bf16_f32 v183, v106, v107
	s_waitcnt lgkmcnt(1)
	v_mfma_f32_32x32x16_bf16 v[132:147], v[12:15], v[172:175], v[132:147]
	v_add_u32_e32 v4, s6, v208
	v_add_u32_e32 v8, s6, v212
	ds_read_b128 v[4:7], v4
	ds_read_b128 v[220:223], v8 offset:4096
	v_add_f32_e32 v3, v108, v3
	v_add_f32_e32 v3, v109, v3
	v_add_f32_e32 v3, v110, v3
	v_add_f32_e32 v3, v111, v3
	v_cvt_pk_bf16_f32 v12, v108, v109
	v_cvt_pk_bf16_f32 v13, v110, v111
	s_waitcnt lgkmcnt(2)
	v_mfma_f32_32x32x16_bf16 v[148:163], v[216:219], v[172:175], v[148:163]
	v_add_f32_e32 v3, v112, v3
	v_add_f32_e32 v3, v113, v3
	v_add_f32_e32 v3, v114, v3
	v_add_f32_e32 v3, v115, v3
	v_cvt_pk_bf16_f32 v14, v112, v113
	v_cvt_pk_bf16_f32 v15, v114, v115
	s_waitcnt lgkmcnt(1)
	v_mfma_f32_32x32x16_bf16 v[132:147], v[4:7], v[168:171], v[132:147]
	v_add_u32_e32 v8, s6, v209
	v_add_u32_e32 v9, s6, v213
	ds_read_b128 v[216:219], v8
	ds_read_b128 v[224:227], v9 offset:4096
	v_add_f32_e32 v3, v116, v3
	v_add_f32_e32 v3, v117, v3
	v_add_f32_e32 v3, v118, v3
	v_add_f32_e32 v3, v119, v3
	v_cvt_pk_bf16_f32 v8, v116, v117
	v_cvt_pk_bf16_f32 v9, v118, v119
	s_waitcnt lgkmcnt(2)
	v_mfma_f32_32x32x16_bf16 v[148:163], v[220:223], v[168:171], v[148:163]
	v_add_f32_e32 v3, v120, v3
	v_add_f32_e32 v3, v121, v3
	v_add_f32_e32 v3, v122, v3
	v_add_f32_e32 v3, v123, v3
	v_cvt_pk_bf16_f32 v10, v120, v121
	v_cvt_pk_bf16_f32 v11, v122, v123
	s_waitcnt lgkmcnt(1)
	v_mfma_f32_32x32x16_bf16 v[132:147], v[216:219], v[164:167], v[132:147]
	v_add_f32_e32 v3, v124, v3
	v_add_f32_e32 v3, v125, v3
	v_add_f32_e32 v3, v126, v3
	v_add_f32_e32 v3, v127, v3
	v_cvt_pk_bf16_f32 v4, v124, v125
	v_cvt_pk_bf16_f32 v5, v126, v127
	s_waitcnt lgkmcnt(0)
	v_mfma_f32_32x32x16_bf16 v[148:163], v[224:227], v[164:167], v[148:163]
	v_add_f32_e32 v3, v128, v3
	v_add_f32_e32 v3, v129, v3
	v_add_f32_e32 v3, v130, v3
	v_add_f32_e32 v3, v131, v3
	v_cvt_pk_bf16_f32 v6, v128, v129
	v_cvt_pk_bf16_f32 v7, v130, v131
	s_mul_hi_u32 s6, s81, 0xcccccccd
	s_lshr_b32 s6, s6, 2
	s_mul_i32 s6, s6, 0x14000
	v_subrev_u32_e32 v243, s6, v215
	ds_read_b64_tr_b16 v[228:229], v243 offset:0
	ds_read_b64_tr_b16 v[230:231], v243 offset:0x800
	ds_read_b64_tr_b16 v[232:233], v243 offset:0x200
	ds_read_b64_tr_b16 v[234:235], v243 offset:0xa00
	ds_read_b64_tr_b16 v[236:237], v243 offset:0x400
	ds_read_b64_tr_b16 v[238:239], v243 offset:0xc00
	ds_read_b64_tr_b16 v[240:241], v243 offset:0x600
	ds_read_b64_tr_b16 v[242:243], v243 offset:0xe00
	s_nop 0
	v_cmp_ge_f32_e32 vcc, s38, v3
	s_cmp_eq_u64 vcc, exec
	s_cbranch_scc0 .LBB0_958

.LBB0_946:
	s_setprio 1
	s_mul_hi_u32 s6, s81, 0xcccccccd
	s_lshr_b32 s6, s6, 2
	s_mul_i32 s6, s6, 0x14000
	v_subrev_u32_e32 v16, s6, v215
	s_cmp_lg_u32 0, -1
	s_cselect_b32 s6, 0, 0
	v_add_u32_e32 v16, s6, v16
	ds_read_b64_tr_b16 v[116:117], v16 offset:0x1000
	ds_read_b64_tr_b16 v[118:119], v16 offset:0x1800
	ds_read_b64_tr_b16 v[120:121], v16 offset:0x1200
	ds_read_b64_tr_b16 v[122:123], v16 offset:0x1a00
	ds_read_b64_tr_b16 v[124:125], v16 offset:0x1400
	ds_read_b64_tr_b16 v[126:127], v16 offset:0x1c00
	ds_read_b64_tr_b16 v[128:129], v16 offset:0x1600
	ds_read_b64_tr_b16 v[130:131], v16 offset:0x1e00
	s_waitcnt lgkmcnt(8)
	s_nop 0
	v_mfma_f32_32x32x16_bf16 v[66:81], v[228:231], v[180:183], v[66:81]
	v_exp_f32_e32 v132, v132
	v_exp_f32_e32 v133, v133
	v_mfma_f32_32x32x16_bf16 v[50:65], v[232:235], v[180:183], v[50:65]
	v_exp_f32_e32 v134, v134
	v_exp_f32_e32 v135, v135
	v_mfma_f32_32x32x16_bf16 v[34:49], v[236:239], v[180:183], v[34:49]
	v_exp_f32_e32 v136, v136
	v_exp_f32_e32 v137, v137
	v_mfma_f32_32x32x16_bf16 v[18:33], v[240:243], v[180:183], v[18:33]
	v_exp_f32_e32 v138, v138
	v_exp_f32_e32 v139, v139
	ds_read_b64_tr_b16 v[100:101], v16 offset:0x2000
	ds_read_b64_tr_b16 v[102:103], v16 offset:0x2800
	ds_read_b64_tr_b16 v[104:105], v16 offset:0x2200
	ds_read_b64_tr_b16 v[106:107], v16 offset:0x2a00
	ds_read_b64_tr_b16 v[108:109], v16 offset:0x2400
	ds_read_b64_tr_b16 v[110:111], v16 offset:0x2c00
	ds_read_b64_tr_b16 v[112:113], v16 offset:0x2600
	ds_read_b64_tr_b16 v[114:115], v16 offset:0x2e00
	s_waitcnt lgkmcnt(8)
	v_mfma_f32_32x32x16_bf16 v[66:81], v[116:119], v[12:15], v[66:81]
	v_exp_f32_e32 v140, v140
	v_exp_f32_e32 v141, v141
	v_mfma_f32_32x32x16_bf16 v[50:65], v[120:123], v[12:15], v[50:65]
	v_exp_f32_e32 v142, v142
	v_exp_f32_e32 v143, v143
	v_mfma_f32_32x32x16_bf16 v[34:49], v[124:127], v[12:15], v[34:49]
	v_exp_f32_e32 v144, v144
	v_exp_f32_e32 v145, v145
	v_mfma_f32_32x32x16_bf16 v[18:33], v[128:131], v[12:15], v[18:33]
	v_exp_f32_e32 v146, v146
	v_exp_f32_e32 v147, v147
	ds_read_b64_tr_b16 v[12:13], v16 offset:0x3000
	ds_read_b64_tr_b16 v[14:15], v16 offset:0x3800
	ds_read_b64_tr_b16 v[116:117], v16 offset:0x3200
	ds_read_b64_tr_b16 v[118:119], v16 offset:0x3a00
	ds_read_b64_tr_b16 v[120:121], v16 offset:0x3400
	ds_read_b64_tr_b16 v[122:123], v16 offset:0x3c00
	ds_read_b64_tr_b16 v[124:125], v16 offset:0x3600
	ds_read_b64_tr_b16 v[126:127], v16 offset:0x3e00
	s_waitcnt lgkmcnt(8)
	v_mfma_f32_32x32x16_bf16 v[66:81], v[100:103], v[8:11], v[66:81]
	v_exp_f32_e32 v148, v148
	v_exp_f32_e32 v149, v149
	v_mfma_f32_32x32x16_bf16 v[50:65], v[104:107], v[8:11], v[50:65]
	v_exp_f32_e32 v150, v150
	v_exp_f32_e32 v151, v151
	v_mfma_f32_32x32x16_bf16 v[34:49], v[108:111], v[8:11], v[34:49]
	v_exp_f32_e32 v152, v152
	v_exp_f32_e32 v153, v153
	v_mfma_f32_32x32x16_bf16 v[18:33], v[112:115], v[8:11], v[18:33]
	v_exp_f32_e32 v154, v154
	v_exp_f32_e32 v155, v155
	s_waitcnt lgkmcnt(0)
	v_mfma_f32_32x32x16_bf16 v[66:81], v[12:15], v[4:7], v[66:81]
	v_exp_f32_e32 v156, v156
	v_exp_f32_e32 v157, v157
	v_mfma_f32_32x32x16_bf16 v[50:65], v[116:119], v[4:7], v[50:65]
	v_exp_f32_e32 v158, v158
	v_exp_f32_e32 v159, v159
	v_mfma_f32_32x32x16_bf16 v[34:49], v[120:123], v[4:7], v[34:49]
	v_exp_f32_e32 v160, v160
	v_exp_f32_e32 v161, v161
	v_mfma_f32_32x32x16_bf16 v[18:33], v[124:127], v[4:7], v[18:33]
	v_exp_f32_e32 v162, v162
	v_exp_f32_e32 v163, v163
.Latt64_skip_h1:
	s_setprio 2
	s_add_i32 s83, s84, 2
	s_cmp_ge_u32 s83, s50
	s_cselect_b64 s[68:69], -1, 0
	s_and_b64 vcc, exec, s[68:69]
	s_cbranch_vccnz .LBB0_948
	s_mul_hi_u32 s6, s13, 0xcccccccd
	s_lshr_b32 s6, s6, 2
	s_mul_i32 s6, s6, 0x14000
	s_sub_i32 s17, s14, s6
	s_min_i32 s6, s83, s49
	s_lshl_b64 s[18:19], s[6:7], 17
	s_add_u32 s20, s52, s18
	s_addc_u32 s21, s53, s19
	s_add_u32 s18, s66, s18
	s_addc_u32 s19, s67, s19
	s_cmp_lg_u32 0, -1
	s_cselect_b32 s6, 0, 0
	s_add_i32 s6, s17, s6
	s_add_i32 s17, s80, 0x4000
	s_and_b32 s17, s17, 0x6000
	s_add_i32 s17, s17, s11
	s_mov_b32 s22, m0
	s_mov_b32 m0, s6
	s_nop 0
	global_load_lds_dwordx4 v194, s[20:21]
	s_mov_b32 m0, s22
	s_add_u32 s20, s20, 0x10000
	s_addc_u32 s21, s21, 0
	s_addk_i32 s6, 0x2000
	s_mov_b32 s22, m0
	s_mov_b32 m0, s6
	s_nop 0
	global_load_lds_dwordx4 v194, s[20:21]
	s_mov_b32 m0, s22
	s_mov_b32 s6, m0
	s_mov_b32 m0, s17
	s_nop 0
	global_load_lds_dwordx4 v195, s[18:19]
	s_mov_b32 m0, s6

.LBB0_950:
	s_setprio 0
	v_add_f32_e32 v16, v3, v184
	s_and_b32 s17, s80, 0x6000
	s_add_i32 s17, s17, 0
	s_add_i32 s17, s17, 0x14000
	v_add_u32_e32 v3, s17, v206
	v_add_u32_e32 v8, s17, v210
	ds_read_b128 v[4:7], v3
	ds_read_b128 v[8:11], v8 offset:4096
	s_waitcnt lgkmcnt(1)
	v_mfma_f32_32x32x16_bf16 v[100:115], v[4:7], v[176:179], v[82:97]
	v_add_u32_e32 v3, s17, v207
	ds_read_b128 v[12:15], v3
	v_add_u32_e32 v3, s17, v211
	ds_read_b128 v[216:219], v3 offset:4096
	v_add_f32_e32 v3, 0, v132
	v_add_f32_e32 v3, v133, v3
	v_add_f32_e32 v3, v134, v3
	v_add_f32_e32 v3, v135, v3
	v_cvt_pk_bf16_f32 v180, v132, v133
	v_cvt_pk_bf16_f32 v181, v134, v135
	s_waitcnt lgkmcnt(2)
	v_mfma_f32_32x32x16_bf16 v[116:131], v[8:11], v[176:179], v[82:97]
	v_add_f32_e32 v3, v136, v3
	v_add_f32_e32 v3, v137, v3
	v_add_f32_e32 v3, v138, v3
	v_add_f32_e32 v3, v139, v3
	v_cvt_pk_bf16_f32 v182, v136, v137
	v_cvt_pk_bf16_f32 v183, v138, v139
	s_waitcnt lgkmcnt(1)
	v_mfma_f32_32x32x16_bf16 v[100:115], v[12:15], v[172:175], v[100:115]
	v_add_u32_e32 v4, s17, v208
	v_add_u32_e32 v8, s17, v212
	ds_read_b128 v[4:7], v4
	ds_read_b128 v[220:223], v8 offset:4096
	v_add_f32_e32 v3, v140, v3
	v_add_f32_e32 v3, v141, v3
	v_add_f32_e32 v3, v142, v3
	v_add_f32_e32 v3, v143, v3
	v_cvt_pk_bf16_f32 v12, v140, v141
	v_cvt_pk_bf16_f32 v13, v142, v143
	s_waitcnt lgkmcnt(2)
	v_mfma_f32_32x32x16_bf16 v[116:131], v[216:219], v[172:175], v[116:131]
	v_add_f32_e32 v3, v144, v3
	v_add_f32_e32 v3, v145, v3
	v_add_f32_e32 v3, v146, v3
	v_add_f32_e32 v3, v147, v3
	v_cvt_pk_bf16_f32 v14, v144, v145
	v_cvt_pk_bf16_f32 v15, v146, v147
	s_waitcnt lgkmcnt(1)
	v_mfma_f32_32x32x16_bf16 v[100:115], v[4:7], v[168:171], v[100:115]
	v_add_u32_e32 v8, s17, v209
	v_add_u32_e32 v9, s17, v213
	ds_read_b128 v[216:219], v8
	ds_read_b128 v[224:227], v9 offset:4096
	v_add_f32_e32 v3, v148, v3
	v_add_f32_e32 v3, v149, v3
	v_add_f32_e32 v3, v150, v3
	v_add_f32_e32 v3, v151, v3
	v_cvt_pk_bf16_f32 v8, v148, v149
	v_cvt_pk_bf16_f32 v9, v150, v151
	s_waitcnt lgkmcnt(2)
	v_mfma_f32_32x32x16_bf16 v[116:131], v[220:223], v[168:171], v[116:131]
	v_add_f32_e32 v3, v152, v3
	v_add_f32_e32 v3, v153, v3
	v_add_f32_e32 v3, v154, v3
	v_add_f32_e32 v3, v155, v3
	v_cvt_pk_bf16_f32 v10, v152, v153
	v_cvt_pk_bf16_f32 v11, v154, v155
	s_waitcnt lgkmcnt(1)
	v_mfma_f32_32x32x16_bf16 v[100:115], v[216:219], v[164:167], v[100:115]
	v_add_f32_e32 v3, v156, v3
	v_add_f32_e32 v3, v157, v3
	v_add_f32_e32 v3, v158, v3
	v_add_f32_e32 v3, v159, v3
	v_cvt_pk_bf16_f32 v4, v156, v157
	v_cvt_pk_bf16_f32 v5, v158, v159
	s_waitcnt lgkmcnt(0)
	v_mfma_f32_32x32x16_bf16 v[116:131], v[224:227], v[164:167], v[116:131]
	v_add_f32_e32 v3, v160, v3
	v_add_f32_e32 v3, v161, v3
	v_add_f32_e32 v3, v162, v3
	v_add_f32_e32 v17, v163, v3
	v_cvt_pk_bf16_f32 v6, v160, v161
	v_cvt_pk_bf16_f32 v7, v162, v163
	s_mul_hi_u32 s17, s92, 0xcccccccd
	s_lshr_b32 s17, s17, 2
	s_mul_i32 s17, s17, 0x14000
	v_subrev_u32_e32 v243, s17, v214
	ds_read_b64_tr_b16 v[228:229], v243 offset:0
	ds_read_b64_tr_b16 v[230:231], v243 offset:0x800
	ds_read_b64_tr_b16 v[232:233], v243 offset:0x200
	ds_read_b64_tr_b16 v[234:235], v243 offset:0xa00
	ds_read_b64_tr_b16 v[236:237], v243 offset:0x400
	ds_read_b64_tr_b16 v[238:239], v243 offset:0xc00
	ds_read_b64_tr_b16 v[240:241], v243 offset:0x600
	ds_read_b64_tr_b16 v[242:243], v243 offset:0xe00
	s_nop 0
	v_cmp_ge_f32_e32 vcc, s38, v17
	s_cmp_eq_u64 vcc, exec
	s_cbranch_scc0 .LBB0_960

.LBB0_955:
.LBB0_956:
	s_setprio 1
	s_mul_hi_u32 s10, s92, 0xcccccccd
	s_lshr_b32 s10, s10, 2
	v_pk_add_f32 v[184:185], v[16:17], v[16:17] op_sel:[1,0] op_sel_hi:[0,1]
	s_mul_i32 s10, s10, 0x14000
	v_subrev_u32_e32 v3, s10, v214
	s_cmp_lg_u32 0, -1
	s_cselect_b32 s10, 0, 0
	v_add_u32_e32 v3, s10, v3
	ds_read_b64_tr_b16 v[148:149], v3 offset:0x1000
	ds_read_b64_tr_b16 v[150:151], v3 offset:0x1800
	ds_read_b64_tr_b16 v[152:153], v3 offset:0x1200
	ds_read_b64_tr_b16 v[154:155], v3 offset:0x1a00
	ds_read_b64_tr_b16 v[156:157], v3 offset:0x1400
	ds_read_b64_tr_b16 v[158:159], v3 offset:0x1c00
	ds_read_b64_tr_b16 v[160:161], v3 offset:0x1600
	ds_read_b64_tr_b16 v[162:163], v3 offset:0x1e00
	s_waitcnt lgkmcnt(8)
	s_nop 0
	v_mfma_f32_32x32x16_bf16 v[66:81], v[228:231], v[180:183], v[66:81]
	v_exp_f32_e32 v100, v100
	v_exp_f32_e32 v101, v101
	v_mfma_f32_32x32x16_bf16 v[50:65], v[232:235], v[180:183], v[50:65]
	v_exp_f32_e32 v102, v102
	v_exp_f32_e32 v103, v103
	v_mfma_f32_32x32x16_bf16 v[34:49], v[236:239], v[180:183], v[34:49]
	v_exp_f32_e32 v104, v104
	v_exp_f32_e32 v105, v105
	v_mfma_f32_32x32x16_bf16 v[18:33], v[240:243], v[180:183], v[18:33]
	v_exp_f32_e32 v106, v106
	v_exp_f32_e32 v107, v107
	ds_read_b64_tr_b16 v[132:133], v3 offset:0x2000
	ds_read_b64_tr_b16 v[134:135], v3 offset:0x2800
	ds_read_b64_tr_b16 v[136:137], v3 offset:0x2200
	ds_read_b64_tr_b16 v[138:139], v3 offset:0x2a00
	ds_read_b64_tr_b16 v[140:141], v3 offset:0x2400
	ds_read_b64_tr_b16 v[142:143], v3 offset:0x2c00
	ds_read_b64_tr_b16 v[144:145], v3 offset:0x2600
	ds_read_b64_tr_b16 v[146:147], v3 offset:0x2e00
	s_waitcnt lgkmcnt(8)
	v_mfma_f32_32x32x16_bf16 v[66:81], v[148:151], v[12:15], v[66:81]
	v_exp_f32_e32 v108, v108
	v_exp_f32_e32 v109, v109
	v_mfma_f32_32x32x16_bf16 v[50:65], v[152:155], v[12:15], v[50:65]
	v_exp_f32_e32 v110, v110
	v_exp_f32_e32 v111, v111
	v_mfma_f32_32x32x16_bf16 v[34:49], v[156:159], v[12:15], v[34:49]
	v_exp_f32_e32 v112, v112
	v_exp_f32_e32 v113, v113
	v_mfma_f32_32x32x16_bf16 v[18:33], v[160:163], v[12:15], v[18:33]
	v_exp_f32_e32 v114, v114
	v_exp_f32_e32 v115, v115
	ds_read_b64_tr_b16 v[12:13], v3 offset:0x3000
	ds_read_b64_tr_b16 v[14:15], v3 offset:0x3800
	ds_read_b64_tr_b16 v[148:149], v3 offset:0x3200
	ds_read_b64_tr_b16 v[150:151], v3 offset:0x3a00
	ds_read_b64_tr_b16 v[152:153], v3 offset:0x3400
	ds_read_b64_tr_b16 v[154:155], v3 offset:0x3c00
	ds_read_b64_tr_b16 v[156:157], v3 offset:0x3600
	ds_read_b64_tr_b16 v[158:159], v3 offset:0x3e00
	s_waitcnt lgkmcnt(8)
	v_mfma_f32_32x32x16_bf16 v[66:81], v[132:135], v[8:11], v[66:81]
	v_exp_f32_e32 v116, v116
	v_exp_f32_e32 v117, v117
	v_mfma_f32_32x32x16_bf16 v[50:65], v[136:139], v[8:11], v[50:65]
	v_exp_f32_e32 v118, v118
	v_exp_f32_e32 v119, v119
	v_mfma_f32_32x32x16_bf16 v[34:49], v[140:143], v[8:11], v[34:49]
	v_exp_f32_e32 v120, v120
	v_exp_f32_e32 v121, v121
	v_mfma_f32_32x32x16_bf16 v[18:33], v[144:147], v[8:11], v[18:33]
	v_exp_f32_e32 v122, v122
	v_exp_f32_e32 v123, v123
	s_waitcnt lgkmcnt(0)
	v_mfma_f32_32x32x16_bf16 v[66:81], v[12:15], v[4:7], v[66:81]
	v_exp_f32_e32 v124, v124
	v_exp_f32_e32 v125, v125
	v_mfma_f32_32x32x16_bf16 v[50:65], v[148:151], v[4:7], v[50:65]
	v_exp_f32_e32 v126, v126
	v_exp_f32_e32 v127, v127
	v_mfma_f32_32x32x16_bf16 v[34:49], v[152:155], v[4:7], v[34:49]
	v_exp_f32_e32 v128, v128
	v_exp_f32_e32 v129, v129
	v_mfma_f32_32x32x16_bf16 v[18:33], v[156:159], v[4:7], v[18:33]
	v_exp_f32_e32 v130, v130
	v_exp_f32_e32 v131, v131
.Latt64_skip_h2:
	s_setprio 2
	s_waitcnt vmcnt(0) lgkmcnt(0)
	s_barrier
	s_addk_i32 s80, 0x4000
	v_add_u32_e32 v214, 0x8000, v214
	s_add_i32 s92, s92, 2
	s_add_i32 s14, s14, 0x8000
	s_add_i32 s13, s13, 2
	v_add_u32_e32 v215, 0x8000, v215
	s_add_i32 s81, s81, 2
	s_add_i32 s15, s15, 0x8000
	s_add_i32 s12, s12, 2
	s_and_b64 vcc, exec, s[68:69]
	s_cbranch_vccnz .LBB0_962
	s_mov_b32 s10, s6
	s_mov_b32 s84, s83
	s_add_i32 s6, s84, 1
	s_cmp_ge_u32 s6, s50
	s_cbranch_scc0 .LBB0_937
	s_branch .LBB0_938

.LBB0_962:
	s_setprio 0
	s_add_i32 s82, s82, s33
	s_cmpk_gt_i32 s82, 0xff41
	s_cselect_b64 s[66:67], -1, 0
	s_cmpk_lt_i32 s82, 0xff42
	s_cselect_b64 vcc, -1, 0
	v_cndmask_b32_e32 v3, 0, v192, vcc
	v_sub_f32_e32 v132, v3, v205
	v_cmp_neq_f32_e32 vcc, v132, v98
	s_cbranch_vccz .LBB0_964
	v_mov_b32_e32 v133, v132
	v_mov_b32_e32 v134, v132
	v_mov_b32_e32 v135, v132
	v_mov_b32_e32 v136, v132
	v_mov_b32_e32 v137, v132
	v_mov_b32_e32 v138, v132
	v_mov_b32_e32 v139, v132
	v_mov_b32_e32 v140, v132
	v_mov_b32_e32 v141, v132
	v_mov_b32_e32 v142, v132
	v_mov_b32_e32 v143, v132
	v_mov_b32_e32 v144, v132
	v_mov_b32_e32 v145, v132
	v_mov_b32_e32 v146, v132
	v_mov_b32_e32 v147, v132
	s_nop 0
	v_mov_b64_e32 v[82:83], v[132:133]
	v_mov_b64_e32 v[84:85], v[134:135]
	v_mov_b64_e32 v[86:87], v[136:137]
	v_mov_b64_e32 v[88:89], v[138:139]
	v_mov_b64_e32 v[90:91], v[140:141]
	v_mov_b64_e32 v[92:93], v[142:143]
	v_mov_b64_e32 v[94:95], v[144:145]
	v_mov_b64_e32 v[96:97], v[146:147]
